# P5 layer 0: CUs holding three attention items hand their 7th-round LRU item to CUs 96..127 (balances attention+LRU item mix)
# baseline (speedup 1.0000x reference)
; #define PHASE(id, ...) do { { const float rcf = 1.f; (void)rcf; __VA_ARGS__ } GSYNC(); if (PROBE == (id)) { { const float rcf = 0.f; (void)rcf; __VA_ARGS__ } GSYNC(); } } while (0)
; __global__ void __launch_bounds__(NTHREADS) mega(Params p_in) {
;     ...
;     PHASE(5, { const int n_att = l == 0 ? 512 + 32 : 512, n_lru = 1088;
;       for (int it = blockIdx.x; it < n_att + n_lru; it += gridDim.x) { if (it < n_att) attn_item(p, l, it); else lru_item(p, l, it - n_att, 0); }
.LBB0_1279:
	s_add_i32 s42, s42, s3
	s_cmpk_eq_u32 s3, 0x100
	s_cbranch_scc0 .Lmy_p5map_done
	v_readlane_b32 s0, v255, 24
	s_cmpk_eq_u32 s0, 0x220
	s_cbranch_scc0 .Lmy_p5map_done
	s_cmpk_lt_u32 s42, 0x600
	s_cbranch_scc1 .Lmy_p5map_done
	s_sub_u32 s0, s42, 0x600
	s_cmpk_lt_u32 s0, 0x20
	s_cbranch_scc0 .Lmy_p5map_hi
	s_add_u32 s42, s42, 0x60
	s_branch .Lmy_p5map_done
.Lmy_p5map_hi:
	s_cmpk_lt_u32 s0, 0x60
	s_cbranch_scc1 .Lmy_p5map_done
	s_cmpk_lt_u32 s0, 0x80
	s_cbranch_scc0 .Lmy_p5map_done
	s_sub_u32 s42, s42, 0x60
.Lmy_p5map_done:
	s_cmp_ge_i32 s42, s2
	s_cbranch_scc1 .LBB0_1390
